# strategy 7.4: one static s_setprio 1 for waves 4-7 at the start of the mixer phase (scan / decode loops, two waves per SIMD)
# baseline (speedup 1.0000x reference)
.LBB0_1664:
	s_or_b64 exec, exec, s[0:1]
	v_readlane_b32 s0, v234, 0
	v_readlane_b32 s2, v234, 2
	v_readlane_b32 s1, v234, 1
	v_readlane_b32 s3, v234, 3
	s_add_u32 s0, s2, 0x32000000
	s_addc_u32 s1, s3, 0
	v_writelane_b32 v233, s0, 21
	s_waitcnt lgkmcnt(0)
	s_barrier
	v_readfirstlane_b32 s99, v183
	s_nop 3
	s_lshr_b32 s99, s99, 6
	s_cmp_ge_u32 s99, 4
	s_cbranch_scc0 .Lprio_mix_done
	s_setprio 1
.Lprio_mix_done:
	v_writelane_b32 v233, s1, 22
	v_readlane_b32 s0, v234, 12
	s_cmpk_lg_i32 s0, 0x100
	v_readlane_b32 s1, v234, 13
	s_cselect_b64 s[2:3], -1, 0
	v_writelane_b32 v233, s2, 23
	s_cmpk_eq_i32 s0, 0x100
	s_mov_b64 s[0:1], -1
	v_writelane_b32 v233, s3, 24
	s_cbranch_scc0 .LBB0_1716
	v_readlane_b32 s0, v234, 15
	s_cmpk_lt_i32 s0, 0x80
	s_cbranch_scc1 .LBB0_1715
	v_readlane_b32 s0, v234, 15
	s_lshl_b32 s0, s0, 9
	v_mov_b32_e32 v0, v183
	s_add_i32 s0, s0, 0xffff0000
	s_nop 0
	v_add_u32_e32 v130, s0, v0
	s_mov_b32 s0, 0x32000
	v_cmp_gt_i32_e32 vcc, s0, v130
	s_and_saveexec_b64 s[0:1], vcc
	s_cbranch_execz .LBB0_1711
	s_mov_b64 s[4:5], 0
	s_mov_b32 s16, 0x66666667
	s_mov_b64 s[6:7], 0x2800
	s_movk_i32 s17, 0x2000
	s_mov_b64 s[8:9], 0x5000
	s_movk_i32 s18, 0x5000
	s_movk_i32 s19, 0x7000
	s_mov_b32 s20, 0x3a00000
	s_mov_b64 s[10:11], 0x4000
	s_movk_i32 s21, 0x7400
	s_movk_i32 s22, 0x1400
	s_movk_i32 s23, 0x1000
	s_movk_i32 s24, 0x3000
	s_movk_i32 s25, 0x6000
	s_mov_b32 s26, 0x8000
	s_mov_b32 s27, 0xa000
	s_mov_b32 s28, 0xb000
	s_mov_b32 s29, 0xc000
	s_mov_b32 s30, 0xd000
	s_mov_b32 s31, 0xf000
	s_mov_b32 s33, 0x10000
	s_mov_b32 s34, 0x11000
	s_mov_b32 s35, 0x21fff
	s_branch .LBB0_1669
